# v50 + RWKV wave 0: solve's first LDS read batch issued right after the XF barrier (before staging/gload), wave 0 at raised priority for the interval
# speedup vs baseline: 1.0149x; 1.0065x over previous
; #define LAS __attribute__((address_space(3)))
; __device__ __forceinline__ void lds_barrier() { asm volatile("s_waitcnt lgkmcnt(0)" ::: "memory"); __builtin_amdgcn_s_barrier(); asm volatile("" ::: "memory"); }
; __device__ __forceinline__ void rwkv_chunk_item(const P& p, const Ctx& c, int seg, int w, bool save) {
;     ...
;     auto lstore = [&](int pb, int tidv) { const int t = tidv >> 5, j0 = (tidv & 31) * 2;
;         LAS bf16_t* EA = (LAS bf16_t*)(OB + pb * OPB + O_EA); LAS bf16_t* EB = (LAS bf16_t*)(OB + pb * OPB + O_EB); LAS bf16_t* EBT = (LAS bf16_t*)(OB + pb * OPB + O_EBT);
;         LAS bf16_t* UV = (LAS bf16_t*)(OB + pb * OPB + O_UV); LAS float* GT = (LAS float*)(OB + pb * OPB + O_GT);
;         *(LAS unsigned*)(EA + t * 72 + j0) = ga; *(LAS unsigned*)(EA + (16 + t) * 72 + j0) = gr;
;         *(LAS unsigned*)(EB + t * 72 + j0) = gb; *(LAS unsigned*)(EB + (16 + t) * 72 + j0) = gk;
;         EBT[j0 * 40 + t] = (bf16_t)(gb & 0xFFFFu); EBT[(j0 + 1) * 40 + t] = (bf16_t)(gb >> 16); EBT[j0 * 40 + 16 + t] = (bf16_t)(gk & 0xFFFFu); EBT[(j0 + 1) * 40 + 16 + t] = (bf16_t)(gk >> 16);
;         UV[j0 * 40 + 16 + t] = (bf16_t)(gv & 0xFFFFu); UV[(j0 + 1) * 40 + 16 + t] = (bf16_t)(gv >> 16); UV[j0 * 40 + t] = 0; UV[(j0 + 1) * 40 + t] = 0;
;         if (tidv < 64) GT[tidv] = gg; };
;     ...
;         lds_barrier();
;         if (ch + 1 < SEGT / 16) lstore(pb ^ 1, tidv);
;         if (ch + 2 < SEGT / 16) gload(ch + 2, tidv);
;         if (c.wv == 0) {
;             float u[16];
; #pragma unroll
;             for (int p2 = 0; p2 < 8; ++p2) { f32x2 acc = (f32x2){XF[c.lane * 17 + 2 * p2], XF[c.lane * 17 + 2 * p2 + 1]};
; #pragma unroll
;                 for (int s2 = 0; s2 < 2 * p2; ++s2) { const f32x2 m = *(const LAS f32x2*)(MABT + s2 * 20 + 2 * p2); acc += (f32x2){u[s2], u[s2]} * m; }
;                 u[2 * p2] = acc.x;
;                 u[2 * p2 + 1] = acc.y + acc.x * MABT[(2 * p2) * 20 + 2 * p2 + 1]; }
.LBB0_890:
	s_waitcnt lgkmcnt(0)
	s_barrier
	s_andn2_b64 vcc, exec, s[70:71]
	s_cbranch_vccnz .Lrw_early_skip
	s_setprio 3
	v_add_u32_e32 v252, 0xdc00, v81
	v_mov_b32_e32 v253, s88
	ds_read2_b32 v[100:101], v252 offset0:0 offset1:1
	ds_read2_b32 v[102:103], v252 offset0:2 offset1:3
	ds_read2_b32 v[52:53], v252 offset0:4 offset1:5
	ds_read2_b32 v[56:57], v252 offset0:6 offset1:7
	ds_read2_b32 v[60:61], v252 offset0:8 offset1:9
	ds_read2_b32 v[64:65], v252 offset0:10 offset1:11
	ds_read2_b32 v[68:69], v252 offset0:12 offset1:13
	ds_read2_b32 v[72:73], v252 offset0:14 offset1:15
	ds_read_b32 v170, v253 offset:22020
	ds_read_b64 v[156:157], v253 offset:22024
	ds_read_b128 v[230:233], v253 offset:22032
	ds_read_b128 v[124:127], v253 offset:22048
	ds_read_b128 v[176:179], v253 offset:22064
	ds_read_b64 v[158:159], v253 offset:22104
	ds_read_b128 v[234:237], v253 offset:22112
	ds_read_b128 v[128:131], v253 offset:22128
	ds_read_b128 v[180:183], v253 offset:22144
	ds_read_b32 v172, v253 offset:22188
	ds_read_b128 v[238:241], v253 offset:22192
	ds_read_b128 v[132:135], v253 offset:22208
	ds_read_b128 v[184:187], v253 offset:22224
	ds_read_b128 v[242:245], v253 offset:22272
	ds_read_b128 v[136:139], v253 offset:22288
	ds_read_b128 v[188:191], v253 offset:22304
.Lrw_early_skip:
	s_cmp_eq_u32 s86, 31
	s_cselect_b64 s[4:5], -1, 0
	s_and_b64 vcc, exec, s[4:5]
	v_ashrrev_i32_e32 v46, 5, v44
	v_lshlrev_b32_e32 v45, 1, v44
	v_cmp_gt_i32_e64 s[2:3], 64, v44
	s_cbranch_vccnz .LBB0_931
	s_xor_b32 s78, s87, 1
	v_and_b32_e32 v47, 62, v45
	s_mulk_i32 s78, 0x5c00
	s_add_i32 s89, s78, 0
	v_mul_lo_u32 v48, v46, s63
	v_lshlrev_b32_e32 v49, 1, v47
	v_mad_u32_u24 v47, v47, 40, v46
	v_add3_u32 v48, s89, v48, v49
	v_lshl_add_u32 v47, v47, 1, s89
	s_waitcnt vmcnt(1)
	ds_write2st64_b32 v48, v71, v76 offset1:9
	ds_write2st64_b32 v48, v74, v75 offset0:18 offset1:27
	ds_write_b16 v47, v74 offset:9216
	ds_write_b16_d16_hi v47, v74 offset:9296
	ds_write_b16 v47, v75 offset:9248
	ds_write_b16_d16_hi v47, v75 offset:9328
	s_waitcnt vmcnt(0)
	ds_write_b16 v47, v79 offset:14368
	ds_write_b16_d16_hi v47, v79 offset:14448
	ds_write_b16 v47, v5 offset:14336
	ds_write_b16 v47, v5 offset:14416
	s_and_saveexec_b64 s[78:79], s[2:3]
	v_lshl_add_u32 v47, v44, 2, s89
	ds_write_b32 v47, v27 offset:23296
	s_or_b64 exec, exec, s[78:79]
	s_cmp_gt_u32 s86, 29
	s_cbranch_scc0 .LBB0_932

; #define LAS __attribute__((address_space(3)))
; __device__ __forceinline__ unsigned pk2(float lo, float hi) { const bf2_t r = __builtin_convertvector((f32x2){lo, hi}, bf2_t); unsigned u; __builtin_memcpy(&u, &r, 4); return u; }
; __device__ __forceinline__ void rwkv_chunk_item(const P& p, const Ctx& c, int seg, int w, bool save) {
;     ...
;         if (c.wv == 0) {
;             float u[16];
; #pragma unroll
;             for (int p2 = 0; p2 < 8; ++p2) { f32x2 acc = (f32x2){XF[c.lane * 17 + 2 * p2], XF[c.lane * 17 + 2 * p2 + 1]};
; #pragma unroll
;                 for (int s2 = 0; s2 < 2 * p2; ++s2) { const f32x2 m = *(const LAS f32x2*)(MABT + s2 * 20 + 2 * p2); acc += (f32x2){u[s2], u[s2]} * m; }
;                 u[2 * p2] = acc.x;
;                 u[2 * p2 + 1] = acc.y + acc.x * MABT[(2 * p2) * 20 + 2 * p2 + 1]; }
;             *(LAS u32x4*)(UV + c.lane * 40) = (u32x4){pk2(u[0], u[1]), pk2(u[2], u[3]), pk2(u[4], u[5]), pk2(u[6], u[7])};
;             *(LAS u32x4*)(UV + c.lane * 40 + 8) = (u32x4){pk2(u[8], u[9]), pk2(u[10], u[11]), pk2(u[12], u[13]), pk2(u[14], u[15])};
;         }
.LBB0_895:
	s_waitcnt lgkmcnt(0)
	v_fma_f32 v46, v170, v100, v101
	v_pk_fma_f32 v[102:103], v[100:101], v[156:157], v[102:103] op_sel_hi:[0,1,1]
	v_pk_fma_f32 v[52:53], v[100:101], v[230:231], v[52:53] op_sel_hi:[0,1,1]
	v_pk_fma_f32 v[56:57], v[100:101], v[232:233], v[56:57] op_sel_hi:[0,1,1]
	v_pk_fma_f32 v[60:61], v[100:101], v[124:125], v[60:61] op_sel_hi:[0,1,1]
	v_pk_fma_f32 v[64:65], v[100:101], v[126:127], v[64:65] op_sel_hi:[0,1,1]
	v_pk_fma_f32 v[68:69], v[100:101], v[176:177], v[68:69] op_sel_hi:[0,1,1]
	v_pk_fma_f32 v[72:73], v[100:101], v[178:179], v[72:73] op_sel_hi:[0,1,1]
	v_pk_fma_f32 v[102:103], v[46:47], v[158:159], v[102:103] op_sel_hi:[0,1,1]
	v_pk_fma_f32 v[52:53], v[46:47], v[234:235], v[52:53] op_sel_hi:[0,1,1]
	v_pk_fma_f32 v[56:57], v[46:47], v[236:237], v[56:57] op_sel_hi:[0,1,1]
	v_pk_fma_f32 v[60:61], v[46:47], v[128:129], v[60:61] op_sel_hi:[0,1,1]
	v_pk_fma_f32 v[64:65], v[46:47], v[130:131], v[64:65] op_sel_hi:[0,1,1]
	v_pk_fma_f32 v[68:69], v[46:47], v[180:181], v[68:69] op_sel_hi:[0,1,1]
	v_pk_fma_f32 v[72:73], v[46:47], v[182:183], v[72:73] op_sel_hi:[0,1,1]
	ds_read_b32 v173, v253 offset:22356
	ds_read_b64 v[160:161], v253 offset:22360
	ds_read_b128 v[140:143], v253 offset:22368
	ds_read_b128 v[192:195], v253 offset:22384
	ds_read_b64 v[162:163], v253 offset:22440
	ds_read_b128 v[144:147], v253 offset:22448
	ds_read_b128 v[196:199], v253 offset:22464
	s_waitcnt lgkmcnt(7)
	v_fma_f32 v50, v172, v102, v103
	v_pk_fma_f32 v[52:53], v[102:103], v[238:239], v[52:53] op_sel_hi:[0,1,1]
	v_pk_fma_f32 v[56:57], v[102:103], v[240:241], v[56:57] op_sel_hi:[0,1,1]
	v_pk_fma_f32 v[60:61], v[102:103], v[132:133], v[60:61] op_sel_hi:[0,1,1]
	v_pk_fma_f32 v[64:65], v[102:103], v[134:135], v[64:65] op_sel_hi:[0,1,1]
	v_pk_fma_f32 v[68:69], v[102:103], v[184:185], v[68:69] op_sel_hi:[0,1,1]
	v_pk_fma_f32 v[72:73], v[102:103], v[186:187], v[72:73] op_sel_hi:[0,1,1]
	v_pk_fma_f32 v[52:53], v[50:51], v[242:243], v[52:53] op_sel_hi:[0,1,1]
	v_pk_fma_f32 v[56:57], v[50:51], v[244:245], v[56:57] op_sel_hi:[0,1,1]
	v_pk_fma_f32 v[60:61], v[50:51], v[136:137], v[60:61] op_sel_hi:[0,1,1]
	v_pk_fma_f32 v[64:65], v[50:51], v[138:139], v[64:65] op_sel_hi:[0,1,1]
	v_pk_fma_f32 v[68:69], v[50:51], v[188:189], v[68:69] op_sel_hi:[0,1,1]
	v_pk_fma_f32 v[72:73], v[50:51], v[190:191], v[72:73] op_sel_hi:[0,1,1]
	ds_read_b32 v174, v253 offset:22524
	ds_read_b128 v[148:151], v253 offset:22528
	ds_read_b128 v[200:203], v253 offset:22544
	ds_read_b128 v[152:155], v253 offset:22608
	ds_read_b128 v[204:207], v253 offset:22624
	s_waitcnt lgkmcnt(5)
	v_fma_f32 v54, v173, v52, v53
	v_pk_fma_f32 v[56:57], v[52:53], v[160:161], v[56:57] op_sel_hi:[0,1,1]
	v_pk_fma_f32 v[60:61], v[52:53], v[140:141], v[60:61] op_sel_hi:[0,1,1]
	v_pk_fma_f32 v[64:65], v[52:53], v[142:143], v[64:65] op_sel_hi:[0,1,1]
	v_pk_fma_f32 v[68:69], v[52:53], v[192:193], v[68:69] op_sel_hi:[0,1,1]
	v_pk_fma_f32 v[72:73], v[52:53], v[194:195], v[72:73] op_sel_hi:[0,1,1]
	v_pk_fma_f32 v[56:57], v[54:55], v[162:163], v[56:57] op_sel_hi:[0,1,1]
	v_pk_fma_f32 v[60:61], v[54:55], v[144:145], v[60:61] op_sel_hi:[0,1,1]
	v_pk_fma_f32 v[64:65], v[54:55], v[146:147], v[64:65] op_sel_hi:[0,1,1]
	v_pk_fma_f32 v[68:69], v[54:55], v[196:197], v[68:69] op_sel_hi:[0,1,1]
	v_pk_fma_f32 v[72:73], v[54:55], v[198:199], v[72:73] op_sel_hi:[0,1,1]
	ds_read_b32 v248, v253 offset:22692
	ds_read_b64 v[164:165], v253 offset:22696
	ds_read_b128 v[208:211], v253 offset:22704
	ds_read_b64 v[166:167], v253 offset:22776
	ds_read_b128 v[218:221], v253 offset:22784
	s_waitcnt lgkmcnt(5)
	v_fma_f32 v58, v174, v56, v57
	v_pk_fma_f32 v[60:61], v[56:57], v[148:149], v[60:61] op_sel_hi:[0,1,1]
	v_pk_fma_f32 v[64:65], v[56:57], v[150:151], v[64:65] op_sel_hi:[0,1,1]
	v_pk_fma_f32 v[68:69], v[56:57], v[200:201], v[68:69] op_sel_hi:[0,1,1]
	v_pk_fma_f32 v[72:73], v[56:57], v[202:203], v[72:73] op_sel_hi:[0,1,1]
	v_pk_fma_f32 v[60:61], v[58:59], v[152:153], v[60:61] op_sel_hi:[0,1,1]
	v_pk_fma_f32 v[64:65], v[58:59], v[154:155], v[64:65] op_sel_hi:[0,1,1]
	v_pk_fma_f32 v[68:69], v[58:59], v[204:205], v[68:69] op_sel_hi:[0,1,1]
	v_pk_fma_f32 v[72:73], v[58:59], v[206:207], v[72:73] op_sel_hi:[0,1,1]
	ds_read_b32 v249, v253 offset:22860
	ds_read_b128 v[222:225], v253 offset:22864
	ds_read_b128 v[226:229], v253 offset:22944
	s_waitcnt lgkmcnt(3)
	v_fma_f32 v62, v248, v60, v61
	v_pk_fma_f32 v[64:65], v[60:61], v[164:165], v[64:65] op_sel_hi:[0,1,1]
	v_pk_fma_f32 v[68:69], v[60:61], v[208:209], v[68:69] op_sel_hi:[0,1,1]
	v_pk_fma_f32 v[72:73], v[60:61], v[210:211], v[72:73] op_sel_hi:[0,1,1]
	v_pk_fma_f32 v[64:65], v[62:63], v[166:167], v[64:65] op_sel_hi:[0,1,1]
	v_pk_fma_f32 v[68:69], v[62:63], v[218:219], v[68:69] op_sel_hi:[0,1,1]
	v_pk_fma_f32 v[72:73], v[62:63], v[220:221], v[72:73] op_sel_hi:[0,1,1]
	ds_read_b32 v250, v253 offset:23028
	ds_read_b64 v[168:169], v253 offset:23032
	ds_read_b64 v[246:247], v253 offset:23112
	s_waitcnt lgkmcnt(3)
	v_fma_f32 v66, v249, v64, v65
	v_pk_fma_f32 v[68:69], v[64:65], v[222:223], v[68:69] op_sel_hi:[0,1,1]
	v_pk_fma_f32 v[72:73], v[64:65], v[224:225], v[72:73] op_sel_hi:[0,1,1]
	v_pk_fma_f32 v[68:69], v[66:67], v[226:227], v[68:69] op_sel_hi:[0,1,1]
	v_pk_fma_f32 v[72:73], v[66:67], v[228:229], v[72:73] op_sel_hi:[0,1,1]
	ds_read_b32 v251, v253 offset:23196
	s_waitcnt lgkmcnt(1)
	v_fma_f32 v120, v250, v68, v69
	v_pk_fma_f32 v[72:73], v[68:69], v[168:169], v[72:73] op_sel_hi:[0,1,1]
	v_pk_fma_f32 v[72:73], v[120:121], v[246:247], v[72:73] op_sel_hi:[0,1,1]
	s_waitcnt lgkmcnt(0)
	v_fma_f32 v122, v251, v72, v73
	v_add_u32_e32 v252, s88, v80
	v_cvt_pk_bf16_f32 v44, v100, v46
	v_cvt_pk_bf16_f32 v45, v102, v50
	v_cvt_pk_bf16_f32 v46, v52, v54
	v_cvt_pk_bf16_f32 v47, v56, v58
	ds_write_b128 v252, v[44:47] offset:14336
	v_cvt_pk_bf16_f32 v44, v60, v62
	v_cvt_pk_bf16_f32 v45, v64, v66
	v_cvt_pk_bf16_f32 v46, v68, v120
	v_cvt_pk_bf16_f32 v47, v72, v122
	ds_write_b128 v252, v[44:47] offset:14352
	s_setprio 0
